# split grid barriers: the XCD generation word is requested behind the attention tile's last internal barrier and checked at the wait (fallback: the original polling loop)
# speedup vs baseline: 1.0088x; 1.0008x over previous
; #define LAS __attribute__((address_space(3)))
; __device__ __forceinline__ unsigned xb_ld(unsigned* p)              { return __hip_atomic_load(p, __ATOMIC_RELAXED, __HIP_MEMORY_SCOPE_AGENT); }
; #define XB_SPIN(cond, bar) do { unsigned _sp = 0; while (cond) { __builtin_amdgcn_s_sleep(1); \
;     if ((++_sp & 255u) == 0u) { if (xb_ld(&(bar)[XB_TMO])) break; if (_sp > XB_SPIN_CAP) { atomicAdd(&(bar)[XB_TMO], 1u); break; } } } } while (0)
;     ...
;         float4 g0[4], g1[4];
; #pragma unroll
;         for (int q4 = 0; q4 < 4; ++q4) { g0[q4] = *(const float4*)(gnorm + hq * 64 + 8 * q4 + 4 * hi); g1[q4] = *(const float4*)(gnorm + hq * 64 + 32 + 8 * q4 + 4 * hi); }
;         __syncthreads();
;         float tot = 0.f;
; #pragma unroll
;         for (int h = 0; h < 8; ++h) tot += SSQ[h * 32 + r];
;         const float sc = iv * rsqrtf(tot * (1.f / 512.f) + EPS);
;         bf16* orow = MIXB + (size_t)tq * D + hq * 64 + 4 * hi;
; #pragma unroll
;         for (int q4 = 0; q4 < 4; ++q4) {
;             uint2 w0, w1;
;             w0.x = pkbf(O0[4 * q4] * sc * g0[q4].x, O0[4 * q4 + 1] * sc * g0[q4].y); w0.y = pkbf(O0[4 * q4 + 2] * sc * g0[q4].z, O0[4 * q4 + 3] * sc * g0[q4].w);
;             w1.x = pkbf(O1[4 * q4] * sc * g1[q4].x, O1[4 * q4 + 1] * sc * g1[q4].y); w1.y = pkbf(O1[4 * q4 + 2] * sc * g1[q4].z, O1[4 * q4 + 3] * sc * g1[q4].w);
;             *(uint2*)(orow + 8 * q4) = w0; *(uint2*)(orow + 32 + 8 * q4) = w1;
;         }
;         __syncthreads();
; __device__ __forceinline__ void xcd_barrier_wait(const XcdBarrier& b, volatile LAS unsigned* genw) {
;     __syncthreads();
;     if (threadIdx.x == 0) {
;         unsigned* bar = b.bar; const unsigned gen = *genw;
;         XB_SPIN(xb_ld(&bar[XB_XGEN(b.x)]) == gen, bar);
;         __builtin_amdgcn_fence(__ATOMIC_ACQUIRE, "agent");
;         asm volatile("s_waitcnt vmcnt(0)" ::: "memory");
.LBB0_357:
	s_or_b64 exec, exec, s[0:1]
	s_ashr_i32 s9, s8, 31
	s_lshl_b64 s[0:1], s[8:9], 1
	v_readlane_b32 s4, v235, 44
	v_readlane_b32 s5, v235, 45
	s_add_u32 s0, s4, s0
	s_addc_u32 s1, s93, s1
	s_lshl_b64 s[4:5], s[8:9], 2
	v_readlane_b32 s8, v235, 0
	v_readlane_b32 s12, v235, 4
	v_readlane_b32 s13, v235, 5
	v_readlane_b32 s16, v235, 8
	v_readlane_b32 s17, v235, 9
	s_mov_b64 s[12:13], s[16:17]
	s_add_u32 s4, s12, s4
	v_ashrrev_i32_e32 v69, 31, v68
	s_addc_u32 s5, s13, s5
	v_lshl_add_u64 v[62:63], v[68:69], 2, s[4:5]
	s_waitcnt lgkmcnt(0)
	global_load_dwordx4 v[34:37], v[62:63], off
	global_load_dwordx4 v[38:41], v[62:63], off offset:128
	global_load_dwordx4 v[42:45], v[62:63], off offset:32
	global_load_dwordx4 v[46:49], v[62:63], off offset:160
	global_load_dwordx4 v[50:53], v[62:63], off offset:64
	global_load_dwordx4 v[54:57], v[62:63], off offset:192
	global_load_dwordx4 v[58:61], v[62:63], off offset:96
	v_lshl_add_u32 v70, v67, 2, 0
	global_load_dwordx4 v[62:65], v[62:63], off offset:224
	v_add_u32_e32 v76, 0x1a000, v70
	s_barrier
	s_mov_b64 s[24:25], exec
	s_mov_b64 exec, s[62:63]
	s_cbranch_execz .Lgenpf_skip1
	s_lshl_b32 s26, s54, 8
	s_add_u32 s26, s90, s26
	s_addc_u32 s27, s91, 0
	v_mov_b32_e32 v201, 0x2000
	global_load_dword v200, v201, s[26:27] offset:1024 sc1
.Lgenpf_skip1:
	s_mov_b64 exec, s[24:25]
	s_nop 0
	s_nop 0
	s_nop 0
	s_nop 0
	s_nop 0
	ds_read2_b32 v[70:71], v76 offset1:32
	ds_read2_b32 v[72:73], v76 offset0:64 offset1:96
	ds_read2_b32 v[74:75], v76 offset0:128 offset1:160
	ds_read2_b32 v[76:77], v76 offset0:192 offset1:224
	v_mov_b32_e32 v78, 0x358637bd
	s_mov_b32 s3, 0x800000
	v_ashrrev_i32_e32 v67, 31, v66
	s_waitcnt lgkmcnt(3)
	v_add_f32_e32 v70, 0, v70
	v_add_f32_e32 v70, v70, v71
	s_waitcnt lgkmcnt(2)
	v_add_f32_e32 v70, v70, v72
	v_add_f32_e32 v70, v70, v73
	s_waitcnt lgkmcnt(1)
	v_add_f32_e32 v70, v70, v74
	v_add_f32_e32 v70, v70, v75
	s_waitcnt lgkmcnt(0)
	v_add_f32_e32 v70, v70, v76
	v_add_f32_e32 v70, v70, v77
	v_fmac_f32_e32 v78, 0x3b000000, v70
	v_mul_f32_e32 v70, 0x4b800000, v78
	v_cmp_gt_f32_e32 vcc, s3, v78
	v_lshlrev_b64 v[66:67], 11, v[66:67]
	v_lshl_add_u64 v[68:69], v[68:69], 1, s[0:1]
	v_cndmask_b32_e32 v70, v78, v70, vcc
	v_rsq_f32_e32 v70, v70
	v_lshl_add_u64 v[66:67], v[68:69], 0, v[66:67]
	v_readlane_b32 s6, v235, 46
	v_readlane_b32 s7, v235, 47
	v_mul_f32_e32 v68, 0x45800000, v70
	v_cndmask_b32_e32 v68, v70, v68, vcc
	v_mul_f32_e32 v68, v1, v68
	v_pk_mul_f32 v[2:3], v[2:3], v[68:69] op_sel_hi:[1,0]
	v_pk_mul_f32 v[4:5], v[4:5], v[68:69] op_sel_hi:[1,0]
	v_pk_mul_f32 v[18:19], v[18:19], v[68:69] op_sel_hi:[1,0]
	v_pk_mul_f32 v[20:21], v[20:21], v[68:69] op_sel_hi:[1,0]
	v_pk_mul_f32 v[6:7], v[6:7], v[68:69] op_sel_hi:[1,0]
	v_pk_mul_f32 v[8:9], v[8:9], v[68:69] op_sel_hi:[1,0]
	v_pk_mul_f32 v[22:23], v[22:23], v[68:69] op_sel_hi:[1,0]
	v_pk_mul_f32 v[24:25], v[24:25], v[68:69] op_sel_hi:[1,0]
	v_pk_mul_f32 v[10:11], v[10:11], v[68:69] op_sel_hi:[1,0]
	v_pk_mul_f32 v[12:13], v[12:13], v[68:69] op_sel_hi:[1,0]
	v_pk_mul_f32 v[26:27], v[26:27], v[68:69] op_sel_hi:[1,0]
	v_pk_mul_f32 v[28:29], v[28:29], v[68:69] op_sel_hi:[1,0]
	v_readlane_b32 s9, v235, 1
	v_readlane_b32 s10, v235, 2
	v_readlane_b32 s11, v235, 3
	v_readlane_b32 s14, v235, 6
	v_readlane_b32 s15, v235, 7
	v_readlane_b32 s18, v235, 10
	v_readlane_b32 s19, v235, 11
	v_readlane_b32 s20, v235, 12
	v_readlane_b32 s21, v235, 13
	v_readlane_b32 s22, v235, 14
	v_readlane_b32 s23, v235, 15
	s_waitcnt vmcnt(7)
	v_pk_mul_f32 v[2:3], v[34:35], v[2:3]
	v_pk_mul_f32 v[4:5], v[36:37], v[4:5]
	s_waitcnt vmcnt(6)
	v_pk_mul_f32 v[18:19], v[38:39], v[18:19]
	v_pk_mul_f32 v[20:21], v[40:41], v[20:21]
	s_waitcnt vmcnt(5)
	v_pk_mul_f32 v[6:7], v[42:43], v[6:7]
	v_pk_mul_f32 v[8:9], v[44:45], v[8:9]
	s_waitcnt vmcnt(4)
	v_pk_mul_f32 v[22:23], v[46:47], v[22:23]
	v_pk_mul_f32 v[24:25], v[48:49], v[24:25]
	s_waitcnt vmcnt(3)
	v_pk_mul_f32 v[10:11], v[50:51], v[10:11]
	v_pk_mul_f32 v[12:13], v[52:53], v[12:13]
	s_waitcnt vmcnt(2)
	v_pk_mul_f32 v[26:27], v[54:55], v[26:27]
	v_pk_mul_f32 v[28:29], v[56:57], v[28:29]
	v_cvt_pk_bf16_f32 v2, v2, v3
	v_cvt_pk_bf16_f32 v3, v4, v5
	v_cvt_pk_bf16_f32 v4, v18, v19
	v_cvt_pk_bf16_f32 v5, v20, v21
	v_cvt_pk_bf16_f32 v6, v6, v7
	v_cvt_pk_bf16_f32 v7, v8, v9
	v_cvt_pk_bf16_f32 v8, v22, v23
	v_cvt_pk_bf16_f32 v9, v24, v25
	v_cvt_pk_bf16_f32 v10, v10, v11
	v_cvt_pk_bf16_f32 v11, v12, v13
	v_cvt_pk_bf16_f32 v12, v26, v27
	v_cvt_pk_bf16_f32 v13, v28, v29
	global_store_dwordx2 v[66:67], v[2:3], off
	global_store_dwordx2 v[66:67], v[4:5], off offset:64
	global_store_dwordx2 v[66:67], v[6:7], off offset:16
	global_store_dwordx2 v[66:67], v[8:9], off offset:80
	global_store_dwordx2 v[66:67], v[10:11], off offset:32
	global_store_dwordx2 v[66:67], v[12:13], off offset:96
	v_pk_mul_f32 v[2:3], v[14:15], v[68:69] op_sel_hi:[1,0]
	v_pk_mul_f32 v[4:5], v[16:17], v[68:69] op_sel_hi:[1,0]
	s_waitcnt vmcnt(7)
	v_pk_mul_f32 v[2:3], v[58:59], v[2:3]
	v_pk_mul_f32 v[4:5], v[60:61], v[4:5]
	v_cvt_pk_bf16_f32 v2, v2, v3
	v_cvt_pk_bf16_f32 v3, v4, v5
	v_pk_mul_f32 v[4:5], v[30:31], v[68:69] op_sel_hi:[1,0]
	v_pk_mul_f32 v[6:7], v[32:33], v[68:69] op_sel_hi:[1,0]
	s_waitcnt vmcnt(6)
	v_pk_mul_f32 v[4:5], v[62:63], v[4:5]
	v_pk_mul_f32 v[6:7], v[64:65], v[6:7]
	v_cvt_pk_bf16_f32 v4, v4, v5
	v_cvt_pk_bf16_f32 v5, v6, v7
	global_store_dwordx2 v[66:67], v[2:3], off offset:48
	global_store_dwordx2 v[66:67], v[4:5], off offset:112
	s_barrier
.LBB0_358:
	s_waitcnt lgkmcnt(0)
	s_barrier
	s_and_saveexec_b64 s[0:1], s[62:63]
	s_cbranch_execz .LBB0_373
	s_add_i32 s3, 0, 0x20170
	v_mov_b32_e32 v1, s3
	s_lshl_b32 s3, s54, 8
	s_add_u32 s4, s90, s3
	s_addc_u32 s5, s91, 0
	s_nop 0
	ds_read_b32 v1, v1
	s_nop 0
	s_nop 0
	s_add_u32 s4, s4, 0x2400
	s_addc_u32 s5, s5, 0
	s_waitcnt vmcnt(0) lgkmcnt(0)
	v_mov_b32_e32 v2, v200
	v_cmp_ne_u32_e32 vcc, v2, v1
	s_cbranch_vccnz .LBB0_372
	s_mov_b32 s3, 1
	v_mov_b32_e32 v2, 0
	s_branch .LBB0_362

; #define LAS __attribute__((address_space(3)))
; __device__ __forceinline__ unsigned xb_ld(unsigned* p)              { return __hip_atomic_load(p, __ATOMIC_RELAXED, __HIP_MEMORY_SCOPE_AGENT); }
; #define XB_SPIN(cond, bar) do { unsigned _sp = 0; while (cond) { __builtin_amdgcn_s_sleep(1); \
;     if ((++_sp & 255u) == 0u) { if (xb_ld(&(bar)[XB_TMO])) break; if (_sp > XB_SPIN_CAP) { atomicAdd(&(bar)[XB_TMO], 1u); break; } } } } while (0)
;     ...
;         float4 g0[4], g1[4];
; #pragma unroll
;         for (int q4 = 0; q4 < 4; ++q4) { g0[q4] = *(const float4*)(gnorm + hq * 64 + 8 * q4 + 4 * hi); g1[q4] = *(const float4*)(gnorm + hq * 64 + 32 + 8 * q4 + 4 * hi); }
;         __syncthreads();
; __device__ __forceinline__ void xcd_barrier_wait(const XcdBarrier& b, volatile LAS unsigned* genw) {
;     __syncthreads();
;     if (threadIdx.x == 0) {
;         unsigned* bar = b.bar; const unsigned gen = *genw;
;         XB_SPIN(xb_ld(&bar[XB_XGEN(b.x)]) == gen, bar);
.LBB0_445:
	s_or_b64 exec, exec, s[0:1]
	s_ashr_i32 s11, s10, 31
	s_lshl_b64 s[0:1], s[10:11], 1
	v_readlane_b32 s4, v235, 44
	v_readlane_b32 s5, v235, 45
	s_add_u32 s0, s4, s0
	s_addc_u32 s1, s93, s1
	s_lshl_b64 s[4:5], s[10:11], 2
	v_readlane_b32 s8, v235, 0
	v_readlane_b32 s12, v235, 4
	v_readlane_b32 s13, v235, 5
	v_readlane_b32 s16, v235, 8
	v_readlane_b32 s17, v235, 9
	s_mov_b64 s[12:13], s[16:17]
	s_add_u32 s4, s12, s4
	v_ashrrev_i32_e32 v69, 31, v68
	s_addc_u32 s5, s13, s5
	v_lshl_add_u64 v[62:63], v[68:69], 2, s[4:5]
	s_waitcnt lgkmcnt(0)
	global_load_dwordx4 v[34:37], v[62:63], off
	global_load_dwordx4 v[38:41], v[62:63], off offset:128
	global_load_dwordx4 v[42:45], v[62:63], off offset:32
	global_load_dwordx4 v[46:49], v[62:63], off offset:160
	global_load_dwordx4 v[50:53], v[62:63], off offset:64
	global_load_dwordx4 v[54:57], v[62:63], off offset:192
	global_load_dwordx4 v[58:61], v[62:63], off offset:96
	v_lshl_add_u32 v70, v71, 2, 0
	global_load_dwordx4 v[62:65], v[62:63], off offset:224
	v_add_u32_e32 v76, 0x1a000, v70
	s_barrier
	s_mov_b64 s[24:25], exec
	s_mov_b64 exec, s[62:63]
	s_cbranch_execz .Lgenpf_skip2
	s_lshl_b32 s26, s54, 8
	s_add_u32 s26, s90, s26
	s_addc_u32 s27, s91, 0
	v_mov_b32_e32 v201, 0x2000
	global_load_dword v200, v201, s[26:27] offset:1024 sc1
